# NA local loops: the 8 serialized bias-table LDS reads per iteration issued together at the loop top (one wait instead of eight)
# speedup vs baseline: 1.0209x; 1.0014x over previous
.LBB0_1016:
	v_add_u32_e32 v194, s11, v110
	ds_read_b32 v194, v194 offset:868
	v_add_u32_e32 v195, s11, v109
	ds_read_b32 v195, v195 offset:868
	v_add_u32_e32 v196, s11, v108
	ds_read_b32 v196, v196 offset:868
	v_add_u32_e32 v197, s11, v107
	ds_read_b32 v197, v197 offset:868
	v_add_u32_e32 v198, s11, v106
	ds_read_b32 v198, v198 offset:868
	v_add_u32_e32 v199, s11, v101
	ds_read_b32 v199, v199 offset:868
	v_add_u32_e32 v200, s11, v100
	ds_read_b32 v200, v200 offset:868
	v_add_u32_e32 v201, s11, v99
	ds_read_b32 v201, v201 offset:868
	v_lshl_add_u64 v[50:51], v[86:87], 0, v[116:117]
	v_add_co_u32_e32 v38, vcc, s66, v50
	s_waitcnt vmcnt(0)
	v_mov_b64_e32 v[146:147], v[6:7]
	v_addc_co_u32_e32 v39, vcc, 0, v51, vcc
	v_add_co_u32_e32 v42, vcc, s67, v50
	v_mov_b64_e32 v[134:135], v[64:65]
	v_mov_b64_e32 v[138:139], v[60:61]
	v_mov_b64_e32 v[142:143], v[56:57]
	v_mov_b64_e32 v[144:145], v[4:5]
	v_lshl_add_u64 v[4:5], v[88:89], 0, v[116:117]
	v_addc_co_u32_e32 v43, vcc, 0, v51, vcc
	v_mov_b64_e32 v[132:133], v[62:63]
	v_mov_b64_e32 v[136:137], v[58:59]
	v_mov_b64_e32 v[140:141], v[54:55]
	global_load_dwordx4 v[62:65], v[4:5], off offset:-512
	global_load_dwordx4 v[58:61], v[4:5], off offset:-448
	global_load_dwordx4 v[54:57], v[4:5], off
	s_nop 0
	global_load_dwordx4 v[4:7], v[4:5], off offset:64
	v_mfma_f32_16x16x32_bf16 v[132:135], v[132:135], v[0:3], 0
	global_load_dwordx4 v[38:41], v[38:39], off offset:128
	v_add_u32_e32 v111, s11, v110
	global_load_dwordx4 v[46:49], v[42:43], off offset:128
	v_add_co_u32_e32 v42, vcc, s77, v50
	v_mfma_f32_16x16x32_bf16 v[132:135], v[136:139], v[10:13], v[132:135]
	s_nop 0
	v_addc_co_u32_e32 v43, vcc, 0, v51, vcc
	v_add_co_u32_e32 v50, vcc, s78, v50
	global_load_dwordx4 v[42:45], v[42:43], off offset:128
	s_nop 0
	v_addc_co_u32_e32 v51, vcc, 0, v51, vcc
	global_load_dwordx4 v[50:53], v[50:51], off offset:128
	v_mfma_f32_16x16x32_bf16 v[136:139], v[140:143], v[0:3], 0
	s_waitcnt lgkmcnt(0)
	v_mov_b32_e32 v111, v194
	v_add_u32_e32 v112, s11, v109
	s_nop 0
	v_mov_b32_e32 v112, v195
	v_add_u32_e32 v113, s11, v108
	v_mfma_f32_16x16x32_bf16 v[136:139], v[144:147], v[10:13], v[136:139]
	s_nop 0
	v_mov_b32_e32 v113, v196
	v_add_u32_e32 v120, s11, v107
	s_nop 0
	v_mov_b32_e32 v120, v197
	v_add_u32_e32 v121, s11, v106
	s_nop 0
	v_mov_b32_e32 v121, v198
	s_nop 0
	v_add_f32_e32 v111, v132, v111
	v_add_f32_e32 v121, v136, v121
	v_cndmask_b32_e64 v132, v241, v121, s[18:19]
	v_add_u32_e32 v121, s11, v101
	v_mov_b32_e32 v121, v199
	s_nop 0
	v_add_f32_e32 v112, v133, v112
	v_add_f32_e32 v121, v137, v121
	v_cndmask_b32_e64 v133, v241, v121, s[16:17]
	v_add_u32_e32 v121, s11, v100
	v_mov_b32_e32 v121, v200
	s_nop 0
	v_add_f32_e32 v113, v134, v113
	v_add_f32_e32 v121, v138, v121
	v_cndmask_b32_e64 v134, v241, v121, s[14:15]
	v_add_u32_e32 v121, s11, v99
	v_mov_b32_e32 v121, v201
	s_nop 0
	v_cndmask_b32_e64 v111, v241, v111, s[26:27]
	v_add_f32_e32 v121, v139, v121
	v_cndmask_b32_e64 v112, v241, v112, s[24:25]
	v_add_f32_e32 v120, v135, v120
	v_cndmask_b32_e64 v135, v241, v121, s[12:13]
	v_cndmask_b32_e64 v113, v241, v113, s[22:23]
	v_cndmask_b32_e64 v120, v241, v120, s[20:21]
	v_sub_f32_e32 v129, v111, v128
	v_sub_f32_e32 v125, v112, v128
	v_sub_f32_e32 v112, v134, v128
	v_sub_f32_e32 v111, v135, v128
	v_sub_f32_e32 v123, v113, v128
	v_sub_f32_e32 v121, v120, v128
	v_sub_f32_e32 v120, v132, v128
	v_sub_f32_e32 v113, v133, v128
	v_max_f32_e32 v134, v112, v111
	v_max_f32_e32 v132, v129, v125
	v_max_f32_e32 v133, v123, v121
	v_max3_f32 v134, v120, v113, v134
	v_max3_f32 v132, v132, v133, v134
	v_cmp_lt_f32_e32 vcc, s89, v132
	s_cbranch_vccz .LBB0_1018
	ds_bpermute_b32 v133, v127, v132
	v_max_f32_e32 v132, v132, v132
	s_waitcnt lgkmcnt(0)
	v_max_f32_e32 v133, v133, v133
	v_max_f32_e32 v132, v132, v133
	ds_bpermute_b32 v133, v126, v132
	s_waitcnt lgkmcnt(0)
	v_max3_f32 v133, v132, v133, 0
	v_exp_f32_e64 v132, -v133
	v_add_f32_e32 v128, v128, v133
	v_sub_f32_e32 v129, v129, v133
	v_sub_f32_e32 v125, v125, v133
	v_mul_f32_e32 v122, v122, v132
	v_pk_mul_f32 v[36:37], v[36:37], v[132:133] op_sel_hi:[1,0]
	v_pk_mul_f32 v[34:35], v[34:35], v[132:133] op_sel_hi:[1,0]
	v_pk_mul_f32 v[32:33], v[32:33], v[132:133] op_sel_hi:[1,0]
	v_pk_mul_f32 v[30:31], v[30:31], v[132:133] op_sel_hi:[1,0]
	v_pk_mul_f32 v[28:29], v[28:29], v[132:133] op_sel_hi:[1,0]
	v_pk_mul_f32 v[26:27], v[26:27], v[132:133] op_sel_hi:[1,0]
	v_pk_mul_f32 v[24:25], v[24:25], v[132:133] op_sel_hi:[1,0]
	v_pk_mul_f32 v[22:23], v[22:23], v[132:133] op_sel_hi:[1,0]
	v_sub_f32_e32 v123, v123, v133
	v_sub_f32_e32 v121, v121, v133
	v_sub_f32_e32 v120, v120, v133
	v_sub_f32_e32 v113, v113, v133
	v_sub_f32_e32 v112, v112, v133
	v_sub_f32_e32 v111, v111, v133

.LBB0_1023:
	v_add_u32_e32 v194, s10, v155
	ds_read_b32 v194, v194 offset:868
	v_add_u32_e32 v195, s10, v154
	ds_read_b32 v195, v195 offset:868
	v_add_u32_e32 v196, s10, v153
	ds_read_b32 v196, v196 offset:868
	v_add_u32_e32 v197, s10, v152
	ds_read_b32 v197, v197 offset:868
	v_add_u32_e32 v198, s10, v151
	ds_read_b32 v198, v198 offset:868
	v_add_u32_e32 v199, s10, v150
	ds_read_b32 v199, v199 offset:868
	v_add_u32_e32 v200, s10, v149
	ds_read_b32 v200, v200 offset:868
	v_add_u32_e32 v201, s10, v148
	ds_read_b32 v201, v201 offset:868
	s_waitcnt vmcnt(7)
	v_mov_b64_e32 v[158:159], v[100:101]
	s_waitcnt vmcnt(6)
	v_mov_b64_e32 v[162:163], v[96:97]
	s_waitcnt vmcnt(5)
	v_mov_b64_e32 v[166:167], v[92:93]
	s_waitcnt vmcnt(4)
	v_mov_b64_e32 v[170:171], v[88:89]
	v_lshl_add_u64 v[70:71], v[120:121], 0, v[116:117]
	v_lshl_add_u64 v[82:83], v[118:119], 0, v[116:117]
	v_mov_b64_e32 v[156:157], v[98:99]
	v_mov_b64_e32 v[160:161], v[94:95]
	v_mov_b64_e32 v[164:165], v[90:91]
	v_mov_b64_e32 v[168:169], v[86:87]
	global_load_dwordx4 v[98:101], v[70:71], off offset:-512
	global_load_dwordx4 v[94:97], v[70:71], off offset:-448
	global_load_dwordx4 v[90:93], v[70:71], off
	global_load_dwordx4 v[86:89], v[70:71], off offset:64
	v_add_co_u32_e32 v70, vcc, s66, v82
	v_mfma_f32_16x16x32_bf16 v[156:159], v[156:159], v[14:17], 0
	s_nop 0
	v_addc_co_u32_e32 v71, vcc, 0, v83, vcc
	v_add_co_u32_e32 v74, vcc, s67, v82
	global_load_dwordx4 v[70:73], v[70:71], off offset:128
	s_nop 0
	v_addc_co_u32_e32 v75, vcc, 0, v83, vcc
	v_add_co_u32_e32 v78, vcc, s77, v82
	global_load_dwordx4 v[74:77], v[74:75], off offset:128
	s_nop 0
	v_addc_co_u32_e32 v79, vcc, 0, v83, vcc
	v_add_co_u32_e32 v82, vcc, s78, v82
	global_load_dwordx4 v[78:81], v[78:79], off offset:128
	s_nop 0
	v_addc_co_u32_e32 v83, vcc, 0, v83, vcc
	global_load_dwordx4 v[82:85], v[82:83], off offset:128
	v_mfma_f32_16x16x32_bf16 v[156:159], v[160:163], v[18:21], v[156:159]
	v_add_u32_e32 v8, s10, v155
	s_waitcnt lgkmcnt(0)
	v_mov_b32_e32 v8, v194
	s_nop 0
	v_mfma_f32_16x16x32_bf16 v[160:163], v[164:167], v[14:17], 0
	v_mfma_f32_16x16x32_bf16 v[160:163], v[168:171], v[18:21], v[160:163]
	s_nop 2
	v_add_f32_e32 v8, v156, v8
	v_add_u32_e32 v156, s10, v154
	v_mov_b32_e32 v156, v195
	s_nop 0
	v_cndmask_b32_e64 v8, v241, v8, s[26:27]
	v_add_f32_e32 v156, v157, v156
	v_add_u32_e32 v157, s10, v153
	v_mov_b32_e32 v157, v196
	s_nop 0
	v_cndmask_b32_e64 v156, v241, v156, s[24:25]
	v_add_f32_e32 v157, v158, v157
	v_add_u32_e32 v158, s10, v152
	v_mov_b32_e32 v158, v197
	s_nop 0
	v_cndmask_b32_e64 v157, v241, v157, s[22:23]
	v_add_f32_e32 v158, v159, v158
	v_add_u32_e32 v159, s10, v151
	v_mov_b32_e32 v159, v198
	s_nop 0
	v_cndmask_b32_e64 v158, v241, v158, s[20:21]
	v_add_f32_e32 v159, v160, v159
	v_cndmask_b32_e64 v164, v241, v159, s[18:19]
	v_add_u32_e32 v159, s10, v150
	v_mov_b32_e32 v159, v199
	s_nop 0
	v_sub_f32_e32 v160, v157, v129
	v_add_f32_e32 v159, v161, v159
	v_cndmask_b32_e64 v165, v241, v159, s[16:17]
	v_add_u32_e32 v159, s10, v149
	v_mov_b32_e32 v159, v200
	s_nop 0
	v_sub_f32_e32 v161, v156, v129
	v_add_f32_e32 v159, v162, v159
	v_cndmask_b32_e64 v166, v241, v159, s[14:15]
	v_add_u32_e32 v159, s10, v148
	v_mov_b32_e32 v159, v201
	s_nop 0
	v_sub_f32_e32 v162, v8, v129
	v_add_f32_e32 v159, v163, v159
	v_cndmask_b32_e64 v163, v241, v159, s[12:13]
	v_sub_f32_e32 v156, v166, v129
	v_sub_f32_e32 v8, v163, v129
	v_sub_f32_e32 v159, v158, v129
	v_sub_f32_e32 v158, v164, v129
	v_sub_f32_e32 v157, v165, v129
	v_max_f32_e32 v165, v156, v8
	v_max_f32_e32 v163, v162, v161
	v_max_f32_e32 v164, v160, v159
	v_max3_f32 v165, v158, v157, v165
	v_max3_f32 v163, v163, v164, v165
	v_cmp_lt_f32_e32 vcc, s89, v163
	s_cbranch_vccz .LBB0_1025
	ds_bpermute_b32 v164, v127, v163
	v_max_f32_e32 v163, v163, v163
	s_waitcnt lgkmcnt(0)
	v_max_f32_e32 v164, v164, v164
	v_max_f32_e32 v163, v163, v164
	ds_bpermute_b32 v164, v126, v163
	s_waitcnt lgkmcnt(0)
	v_max3_f32 v163, v163, v164, 0
	v_exp_f32_e64 v164, -v163
	v_add_f32_e32 v129, v129, v163
	v_sub_f32_e32 v162, v162, v163
	v_sub_f32_e32 v161, v161, v163
	v_mul_f32_e32 v123, v123, v164
	v_pk_mul_f32 v[6:7], v[6:7], v[164:165] op_sel_hi:[1,0]
	v_pk_mul_f32 v[4:5], v[4:5], v[164:165] op_sel_hi:[1,0]
	v_pk_mul_f32 v[68:69], v[68:69], v[164:165] op_sel_hi:[1,0]
	v_pk_mul_f32 v[66:67], v[66:67], v[164:165] op_sel_hi:[1,0]
	v_pk_mul_f32 v[64:65], v[64:65], v[164:165] op_sel_hi:[1,0]
	v_pk_mul_f32 v[62:63], v[62:63], v[164:165] op_sel_hi:[1,0]
	v_pk_mul_f32 v[60:61], v[60:61], v[164:165] op_sel_hi:[1,0]
	v_pk_mul_f32 v[58:59], v[58:59], v[164:165] op_sel_hi:[1,0]
	v_sub_f32_e32 v160, v160, v163
	v_sub_f32_e32 v159, v159, v163
	v_sub_f32_e32 v158, v158, v163
	v_sub_f32_e32 v157, v157, v163
	v_sub_f32_e32 v156, v156, v163
	v_sub_f32_e32 v8, v8, v163
